# v32 + groups 2,3: gate-column units of the input projection deferred to the short-item workgroups of the prep phase; 384 early units in the branch phase of groups 1,2; output/input projection phase ha
# speedup vs baseline: 1.0023x; 1.0010x over previous
; #define TIDV tid_opaque()
; #define BIDX bid_opaque()
; #define GDIM gdim_opaque()
;     DI bool next(int i, Unit& u) const { if (!S.next(i / 3, u)) return false; const int z = i % 3; u.z = z; u.offA = (unsigned)z * (unsigned)(G0ROWS * 512 * 2); u.offB = (unsigned)z * (unsigned)(524288 * 2); return true; }
;     DI bool next(int i, Unit& u) const { const int j = i * G + c; if (j >= 3 * 4 * NKSL) return false; u.pm = MMAIN / 256 + j / (4 * NKSL); u.pn = (j / NKSL) & 3; const int kh = j % NKSL; u.z = kh; u.offA = (unsigned)(kh * 512); u.offB = (unsigned)(kh * 512); return true; }
;     __host__ __device__ bool next(int i, Unit& u) const {
;         const long L = (long)i * G + c; if (L >= nwg) return false;
;         int wgid = (int)L; { const int q = nwg / NXCD, r = nwg % NXCD, xcd = wgid % NXCD, off = wgid / NXCD; wgid = (xcd < r ? xcd * (q + 1) : r * (q + 1) + (xcd - r) * q) + off; }
;         const int nig = WGM * nN, gid = wgid / nig, fm = gid * WGM, gsz = (nM - fm) < WGM ? (nM - fm) : WGM;
;         u.pm = fm + ((wgid % nig) % gsz); u.pn = (wgid % nig) / gsz; return true;
; template <int KIND> DI void run_phase(PARAMS P, int l, int g) {
;     ...
;     else if constexpr (KIND == 7) {
;         { pg8::Gemm gm{(const bf16_t*)((unsigned char*)P.out + DS_MIXB), wl + WL_WOUT, gr, D, D}; pg8::StaticOrder S; S.init(gr, D, GDIM, (BIDX + GDIM / 2) % GDIM);
;           EpiRes E{X + (size_t)gbs * D}; pg8::gemm_phase<EpiRes, pg8::StaticOrder, true, true>(TIDV, lds, gm, S, E); }
;         if (g < NGROUP - 1) { const int g2 = g + 1, gr2 = grows(g2), gbs2 = gbase(g2);
;           pg8::Gemm gm{XN + (size_t)gbs2 * D, wl + WL_WIN, gr2, NIN, D}; pg8::StaticOrder S; S.init(gr2, NIN, GDIM, BIDX);
;           EpiIn E{gb, (const float*)(P.ws + WS_ROT), g2}; pg8::gemm_phase<EpiIn, pg8::StaticOrder, true, true>(TIDV, lds, gm, S, E); }
.Lk7_noff:
	s_mov_b32 s98, 0
	s_cmp_lg_u32 s92, 0x100
	s_cbranch_scc1 .Lk7_go
	s_cmp_gt_u32 s34, 2
	s_cbranch_scc1 .Lk7_go
	s_cmp_eq_u32 s34, 0
	s_cbranch_scc1 .Lk7_mode_g0
	s_mov_b32 s98, 1
	s_mov_b32 s99, 0x90000180
	s_cmp_eq_u32 s31, 6
	s_cbranch_scc0 .Lk7_go
	s_mov_b32 s98, 2
	s_mov_b32 s99, 0x418080
	s_branch .Lk7_go
.Lk7_mode_g0:
	s_mov_b32 s98, 1
	s_mov_b32 s99, 0xc9100260
	s_cmp_eq_u32 s31, 6
	s_cbranch_scc0 .Lk7_go
	s_mov_b32 s98, 2
	s_mov_b32 s99, 0x61208c
.Lk7_go:
	s_load_dwordx4 s[4:7], s[18:19], 0xe8
	s_mul_i32 s1, s96, 0x2400000
	s_mul_hi_i32 s0, s96, 0x2400000
	s_waitcnt vmcnt(0)
	v_mov_b32_e32 v0, v228
	s_waitcnt lgkmcnt(0)
	s_add_u32 s1, s6, s1
	s_addc_u32 s0, s7, s0
	s_add_u32 s35, s1, 0xc480000
	s_addc_u32 s74, s0, 0
	s_cmp_eq_u32 s34, 0
	s_cselect_b64 s[38:39], -1, 0
	s_and_b64 s[0:1], s[38:39], exec
	v_mov_b32_e32 v0, v228
	s_mov_b32 s10, s92
	s_mov_b32 s1, s92
	s_mov_b32 s2, s82
	s_mov_b32 s3, s92
	s_cselect_b32 s0, 35, 32
	s_abs_i32 s10, s10
	v_cvt_f32_u32_e32 v0, s10
	s_lshr_b32 s11, s3, 31
	s_add_i32 s3, s3, s11
	s_sub_i32 s11, 0, s10
	v_rcp_iflag_f32_e32 v0, v0
	s_ashr_i32 s3, s3, 1
	s_add_i32 s3, s3, s2
	s_ashr_i32 s2, s3, 31
	v_mul_f32_e32 v0, 0x4f7ffffe, v0
	v_cvt_u32_f32_e32 v0, v0
	s_abs_i32 s3, s3
	v_writelane_b32 v254, s68, 24
	v_mov_b32_e32 v14, v228
	v_readfirstlane_b32 s12, v0
	s_mul_i32 s11, s11, s12
	s_mul_hi_u32 s11, s12, s11
	s_add_i32 s12, s12, s11
	s_mul_hi_u32 s11, s3, s12
	s_mul_i32 s11, s11, s10
	s_sub_i32 s3, s3, s11
	s_sub_i32 s11, s3, s10
	s_cmp_ge_u32 s3, s10
	s_cselect_b32 s3, s11, s3
	s_sub_i32 s11, s3, s10
	s_cmp_ge_u32 s3, s10
	s_cselect_b32 s3, s11, s3
	s_xor_b32 s3, s3, s2
	s_sub_i32 s2, s3, s2
	s_lshl_b32 s12, s0, 2
	v_writelane_b32 v254, s69, 25
	s_cmp_ge_i32 s2, s12
	v_readfirstlane_b32 s33, v14
	s_cbranch_scc1 .LBB0_227
	s_cmp_ge_u32 s98, 2
	s_cbranch_scc1 .LBB0_227
	s_ashr_i32 s11, s2, 31
	s_lshr_b32 s16, s11, 29
	s_add_i32 s36, s2, s16
	s_lshr_b32 s3, s0, 1
	s_and_b32 s16, s36, -8
	s_mov_b64 s[94:95], s[18:19]
	s_and_b32 s10, s12, 4
	s_sub_i32 s21, s2, s16
	s_add_i32 s18, s3, 1
	s_cmp_ge_i32 s21, s10
	s_mov_b64 s[16:17], -1
	s_mul_i32 s19, s18, s10
	s_cbranch_scc0 .LBB0_206
	s_sub_i32 s16, s21, s10
	s_mul_i32 s16, s16, s3
	s_add_i32 s20, s16, s19
	s_mov_b64 s[16:17], 0

;     DI bool next(int i, Unit& u) const { if (!S.next(i / 3, u)) return false; const int z = i % 3; u.z = z; u.offA = (unsigned)z * (unsigned)(G0ROWS * 512 * 2); u.offB = (unsigned)z * (unsigned)(524288 * 2); return true; }
;     DI bool next(int i, Unit& u) const { const int j = i * G + c; if (j >= 3 * 4 * NKSL) return false; u.pm = MMAIN / 256 + j / (4 * NKSL); u.pn = (j / NKSL) & 3; const int kh = j % NKSL; u.z = kh; u.offA = (unsigned)(kh * 512); u.offB = (unsigned)(kh * 512); return true; }
;     __host__ __device__ bool next(int i, Unit& u) const {
;         const long L = (long)i * G + c; if (L >= nwg) return false;
;         int wgid = (int)L; { const int q = nwg / NXCD, r = nwg % NXCD, xcd = wgid % NXCD, off = wgid / NXCD; wgid = (xcd < r ? xcd * (q + 1) : r * (q + 1) + (xcd - r) * q) + off; }
;         const int nig = WGM * nN, gid = wgid / nig, fm = gid * WGM, gsz = (nM - fm) < WGM ? (nM - fm) : WGM;
;         u.pm = fm + ((wgid % nig) % gsz); u.pn = (wgid % nig) / gsz; return true;
.LBB0_234:
	s_cmp_eq_u32 s98, 0
	s_cbranch_scc1 .Lgi_a_done
	s_cmp_eq_u32 s98, 2
	s_cbranch_scc1 .Lgi_a_early
	s_cmp_eq_u32 s98, 3
	s_cbranch_scc1 .Lgi_a_def
	s_mov_b32 s2, 0
	s_bfe_u32 s3, s99, 0x80010
	s_sub_i32 s3, s79, s3
	s_and_b32 s3, s3, 0xff
	s_add_i32 s2, s2, s3
	s_and_b32 s3, s99, 0xffff
	s_cmp_lt_u32 s2, s3
	s_cselect_b64 s[16:17], -1, 0
	s_cbranch_scc0 .Lgi_a_done
	s_and_b32 s3, s2, 7
	s_lshr_b32 s2, s2, 3
	s_lshl_b32 s3, s3, 2
	s_and_b32 s10, s2, 3
	s_add_i32 s4, s3, s10
	s_lshr_b32 s40, s2, 2
	s_lshr_b32 s3, s99, 29
	s_cmp_lt_u32 s40, s3
	s_cbranch_scc1 .Lgi_a_done
	s_bfe_u32 s3, s99, 0x50018
	s_add_i32 s40, s40, s3
	s_branch .Lgi_a_done
.Lgi_a_def:
	s_lshr_b32 s2, s79, 1
	s_mov_b64 s[16:17], -1
	s_and_b32 s3, s2, 7
	s_lshr_b32 s2, s2, 3
	s_lshl_b32 s3, s3, 2
	s_and_b32 s10, s2, 3
	s_add_i32 s4, s3, s10
	s_lshr_b32 s2, s2, 2
	s_bfe_u32 s3, s99, 0x50014
	s_add_i32 s40, s2, s3
	s_branch .Lgi_a_done
.Lgi_a_early:
	s_and_b32 s3, s99, 0xff
	s_sub_i32 s2, s79, s3
	s_bfe_u32 s3, s99, 0xc0008
	s_cmp_lt_u32 s2, s3
	s_cselect_b64 s[16:17], -1, 0
	s_and_b32 s3, s2, 7
	s_lshr_b32 s2, s2, 3
	s_lshl_b32 s3, s3, 2
	s_and_b32 s10, s2, 3
	s_add_i32 s4, s3, s10
	s_lshr_b32 s2, s2, 2
	s_bfe_u32 s3, s99, 0x50014
	s_add_i32 s40, s2, s3

;     DI bool next(int i, Unit& u) const { if (!S.next(i / 3, u)) return false; const int z = i % 3; u.z = z; u.offA = (unsigned)z * (unsigned)(G0ROWS * 512 * 2); u.offB = (unsigned)z * (unsigned)(524288 * 2); return true; }
;     DI bool next(int i, Unit& u) const { const int j = i * G + c; if (j >= 3 * 4 * NKSL) return false; u.pm = MMAIN / 256 + j / (4 * NKSL); u.pn = (j / NKSL) & 3; const int kh = j % NKSL; u.z = kh; u.offA = (unsigned)(kh * 512); u.offB = (unsigned)(kh * 512); return true; }
;     __host__ __device__ bool next(int i, Unit& u) const {
;         const long L = (long)i * G + c; if (L >= nwg) return false;
;         int wgid = (int)L; { const int q = nwg / NXCD, r = nwg % NXCD, xcd = wgid % NXCD, off = wgid / NXCD; wgid = (xcd < r ? xcd * (q + 1) : r * (q + 1) + (xcd - r) * q) + off; }
;         const int nig = WGM * nN, gid = wgid / nig, fm = gid * WGM, gsz = (nM - fm) < WGM ? (nM - fm) : WGM;
;         u.pm = fm + ((wgid % nig) % gsz); u.pn = (wgid % nig) / gsz; return true;
; template <class Epi, class Sched, bool ALIGN_EPI = false, bool SP2 = false>
; __device__ __forceinline__ void gemm_phase(const int tid, PG8_LAS unsigned char* lds, const Gemm g, const Sched& S, const Epi& E) {
;     ...
;         const bool has_next = S.next(ui + 1, nxt);
;         const char* nA = has_next ? (const char*)g.A + (size_t)nxt.pm * tstep + nxt.offA : cA; const char* nB = has_next ? (const char*)g.Bt + (size_t)nxt.pn * tstep + nxt.offB : cB;
.LBB0_240:
	s_add_i32 s36, s36, 1
	s_cmp_eq_u32 s98, 0
	s_cbranch_scc1 .Lgi_b_orig
	s_cmp_eq_u32 s98, 2
	s_cbranch_scc1 .Lgi_b_early
	s_cmp_eq_u32 s98, 3
	s_cbranch_scc1 .Lgi_b_none
	s_mul_i32 s0, s36, s78
	s_bfe_u32 s1, s99, 0x80010
	s_sub_i32 s1, s79, s1
	s_and_b32 s1, s1, 0xff
	s_add_i32 s0, s0, s1
	s_and_b32 s1, s99, 0xffff
	s_cmp_lt_u32 s0, s1
	s_cselect_b64 s[38:39], -1, 0
	s_cbranch_scc0 .Lgi_b_done
	s_and_b32 s1, s0, 7
	s_lshr_b32 s0, s0, 3
	s_lshl_b32 s1, s1, 2
	s_and_b32 s2, s0, 3
	s_add_i32 s56, s1, s2
	s_lshr_b32 s54, s0, 2
	s_lshr_b32 s1, s99, 29
	s_cmp_lt_u32 s54, s1
	s_cbranch_scc1 .Lgi_b_done
	s_bfe_u32 s1, s99, 0x50018
	s_add_i32 s54, s54, s1
	s_branch .Lgi_b_done
.Lgi_b_none:
	s_mov_b64 s[38:39], 0
	s_branch .Lgi_b_done
.Lgi_b_early:
	s_and_b32 s1, s99, 0xff
	s_sub_i32 s0, s78, s1
	s_mul_i32 s0, s0, s36
	s_add_i32 s0, s0, s79
	s_sub_i32 s0, s0, s1
	s_bfe_u32 s1, s99, 0xc0008
	s_cmp_lt_u32 s0, s1
	s_cselect_b64 s[38:39], -1, 0
	s_cbranch_scc0 .Lgi_b_done
	s_and_b32 s1, s0, 7
	s_lshr_b32 s0, s0, 3
	s_lshl_b32 s1, s1, 2
	s_and_b32 s2, s0, 3
	s_add_i32 s56, s1, s2
	s_lshr_b32 s0, s0, 2
	s_bfe_u32 s1, s99, 0x50014
	s_add_i32 s54, s0, s1

; #define TIDV tid_opaque()
; #define BIDX bid_opaque()
; #define GDIM gdim_opaque()
; DI void prep_phase(PARAMS P, int l, int g, LAS unsigned char* lds, int wave, int lane) {
;     ...
;         __syncthreads();
;     }
; }
; template <int KIND> DI void run_phase(PARAMS P, int l, int g) {
;     ...
;         if (g < NGROUP - 1) { const int g2 = g + 1, gr2 = grows(g2), gbs2 = gbase(g2);
;           pg8::Gemm gm{XN + (size_t)gbs2 * D, wl + WL_WIN, gr2, NIN, D}; pg8::StaticOrder S; S.init(gr2, NIN, GDIM, BIDX);
;           EpiIn E{gb, (const float*)(P.ws + WS_ROT), g2}; pg8::gemm_phase<EpiIn, pg8::StaticOrder, true, true>(TIDV, lds, gm, S, E); }
.LBB0_754:
	v_readlane_b32 s86, v254, 14
	v_readlane_b32 s36, v254, 18
	v_readlane_b32 s78, v254, 20
	v_readlane_b32 s68, v254, 24
	v_readlane_b32 s82, v254, 13
	v_readlane_b32 s87, v254, 15
	v_readlane_b32 s83, v254, 16
	v_readlane_b32 s90, v254, 17
	v_readlane_b32 s37, v254, 19
	v_readlane_b32 s79, v254, 21
	s_movk_i32 s91, 0x1600
	s_movk_i32 s64, 0x2210
	s_mov_b64 s[18:19], s[72:73]
	v_readlane_b32 s69, v254, 25
	s_cmp_lg_u32 s92, 0x100
	s_cbranch_scc1 .Lprep_nodef
	s_add_i32 s99, s34, -2
	s_cmp_gt_u32 s99, 1
	s_cbranch_scc1 .Lprep_nodef
	s_bitcmp0_b32 s82, 0
	s_cbranch_scc0 .Lprep_nodef
	s_add_i32 s34, s34, -1
	s_mov_b32 s98, 3
	s_mov_b32 s99, 0x1008000
	s_branch .Lk7_go
.Lprep_nodef:
.LBB0_755:
	s_mov_b64 s[4:5], 0
